# P0: w_in/w_up/w_fd transposes use a per-wave LDS transpose (no block barriers, waves independent)
# speedup vs baseline: 1.0037x; 1.0037x over previous
; DI void transpose_tile(unsigned char* smem, const int tid, const float* src, int K, int N, bf16_t* dst, int ldd, int permid, int kt, int nt) {
;     float (*tile)[65] = (float (*)[65])smem;
;     const int k0 = kt * 64, n0 = nt * 64;
;     float tv[16];
; #pragma unroll
;     for (int i = 0; i < 16; ++i) {
;         int kk = i * 4 + (tid >> 6), nn = tid & 63;
;         tv[i] = (n0 + nn < N) ? src[(size_t)(k0 + kk) * N + n0 + nn] : 0.f;
;     }
; #pragma unroll
;     for (int i = 0; i < 16; ++i) tile[tid & 63][i * 4 + (tid >> 6)] = tv[i];
;     __syncthreads();
; #pragma unroll 4
;     for (int i = 0; i < 16; ++i) {
;         int nn = i * 4 + (tid >> 6), kk = tid & 63;
;         int n = n0 + nn;
;         if (n < N) {
;             int row = n;
;             if (permid == 1) row = (n < 2048) ? n : ((n >= 2056) ? n - 8 : -1);
; DI void phase0(const Params& p, unsigned char* smem, const int tid, const int vb, const int nvb) {
;     ...
;         if (it < NTR) {
;             int id = it;
;             if (id < 1168) { transpose_tile(smem, tid, p.in[4], 1024, 4616, (bf16_t*)(ws + OFF_WIN), 1024, 1, id / 73, id % 73); continue; }
;             id -= 1168;
;             if (id < 64) {
;                 int isk = id >> 5, r = id & 31, h = r >> 3, t = r & 7;
;                 transpose_tile(smem, tid, (isk ? p.in[9] : p.in[8]) + (size_t)h * 256 * 128, 256, 128,
;                                (bf16_t*)(ws + OFF_WQK) + (size_t)h * 65536 + (isk ? 128 * 256 : 0), 256, 0, t >> 1, t & 1);
;                 continue;
;             }
;             id -= 64;
;             if (id < 256) { transpose_tile(smem, tid, p.in[11], 1024, 1024, (bf16_t*)(ws + OFF_WDN), 1024, 0, id >> 4, id & 15); continue; }
;             id -= 256;
;             if (id < 256) { transpose_tile(smem, tid, p.in[20], 512, 2048, (bf16_t*)(ws + OFF_WGL), 512, 2, id >> 5, id & 31); continue; }
;             id -= 256;
;             if (id < 256) { transpose_tile(smem, tid, p.in[21], 1024, 1024, (bf16_t*)(ws + OFF_WMX), 1024, 0, id >> 4, id & 15); continue; }
;             id -= 256;
;             if (id < 1408) { transpose_tile(smem, tid, p.in[24], 1024, 5632, (bf16_t*)(ws + OFF_WUP), 1024, 3, id / 88, id % 88); continue; }
;             id -= 1408;
;             transpose_tile(smem, tid, p.in[27], 2816, 1024, (bf16_t*)(ws + OFF_WFD), 2816, 0, id >> 4, id & 15);
.LBB0_38:
	s_andn2_saveexec_b64 s[22:23], s[22:23]
	s_cbranch_execz .LBB0_21
	s_movk_i32 s4, 0x48f
	v_cmp_lt_i32_e32 vcc, s4, v4
	s_and_saveexec_b64 s[4:5], vcc
	s_xor_b64 s[24:25], exec, s[4:5]
	s_cbranch_execz .LBB0_89
	s_movk_i32 s4, 0x4cf
	v_cmp_lt_u32_e32 vcc, s4, v4
	s_and_saveexec_b64 s[4:5], vcc
	s_xor_b64 s[26:27], exec, s[4:5]
	s_cbranch_execz .LBB0_84
	s_movk_i32 s4, 0x5cf
	v_cmp_lt_u32_e32 vcc, s4, v4
	s_and_saveexec_b64 s[4:5], vcc
	s_xor_b64 s[28:29], exec, s[4:5]
	s_cbranch_execz .LBB0_79
	s_movk_i32 s4, 0x6cf
	v_cmp_lt_u32_e32 vcc, s4, v4
	s_and_saveexec_b64 s[4:5], vcc
	s_xor_b64 s[30:31], exec, s[4:5]
	s_cbranch_execz .LBB0_66
	s_movk_i32 s4, 0x7cf
	v_cmp_lt_u32_e32 vcc, s4, v4
	s_and_saveexec_b64 s[4:5], vcc
	s_xor_b64 s[34:35], exec, s[4:5]
	s_cbranch_execz .LBB0_61
	s_movk_i32 s4, 0xd4f
	v_cmp_lt_u32_e32 vcc, s4, v4
	s_and_saveexec_b64 s[4:5], vcc
	s_xor_b64 s[4:5], exec, s[4:5]
	s_cbranch_execz .LBB0_48
	v_add_u32_e32 v188, 0xfffff2b0, v4
	v_and_b32_e32 v189, 15, v188
	v_lshrrev_b32_e32 v188, 4, v188
	v_lshlrev_b32_e32 v190, 6, v189
	v_lshlrev_b32_e32 v192, 6, v188
	v_lshrrev_b32_e32 v191, 4, v64
	v_and_b32_e32 v197, 15, v64
	v_lshl_add_u32 v198, v66, 4, v190
	v_add_u32_e32 v199, v192, v191
	v_mul_u32_u24_e32 v193, 0x400, v199
	v_lshlrev_b32_e32 v196, 6, v191
	v_add_lshl_u32 v193, v193, v198, 2
	v_sub_u32_e32 v193, v193, v196
	v_add_co_u32_e32 v194, vcc, v84, v193
	s_mov_b64 s[88:89], 0x4000
	s_nop 0
	v_addc_co_u32_e32 v195, vcc, 0, v85, vcc
	global_load_dword v164, v[194:195], off
	v_lshl_add_u64 v[194:195], v[194:195], 0, s[88:89]
	global_load_dword v165, v[194:195], off
	v_lshl_add_u64 v[194:195], v[194:195], 0, s[88:89]
	global_load_dword v166, v[194:195], off
	v_lshl_add_u64 v[194:195], v[194:195], 0, s[88:89]
	global_load_dword v167, v[194:195], off
	v_lshl_add_u64 v[194:195], v[194:195], 0, s[88:89]
	global_load_dword v168, v[194:195], off
	v_lshl_add_u64 v[194:195], v[194:195], 0, s[88:89]
	global_load_dword v169, v[194:195], off
	v_lshl_add_u64 v[194:195], v[194:195], 0, s[88:89]
	global_load_dword v170, v[194:195], off
	v_lshl_add_u64 v[194:195], v[194:195], 0, s[88:89]
	global_load_dword v171, v[194:195], off
	v_lshl_add_u64 v[194:195], v[194:195], 0, s[88:89]
	global_load_dword v172, v[194:195], off
	v_lshl_add_u64 v[194:195], v[194:195], 0, s[88:89]
	global_load_dword v173, v[194:195], off
	v_lshl_add_u64 v[194:195], v[194:195], 0, s[88:89]
	global_load_dword v174, v[194:195], off
	v_lshl_add_u64 v[194:195], v[194:195], 0, s[88:89]
	global_load_dword v175, v[194:195], off
	v_lshl_add_u64 v[194:195], v[194:195], 0, s[88:89]
	global_load_dword v176, v[194:195], off
	v_lshl_add_u64 v[194:195], v[194:195], 0, s[88:89]
	global_load_dword v177, v[194:195], off
	v_lshl_add_u64 v[194:195], v[194:195], 0, s[88:89]
	global_load_dword v178, v[194:195], off
	v_lshl_add_u64 v[194:195], v[194:195], 0, s[88:89]
	global_load_dword v179, v[194:195], off
	v_lshrrev_b32_e32 v196, 8, v250
	v_mul_u32_u24_e32 v193, 0x1100, v66
	v_lshlrev_b32_e32 v196, 16, v196
	v_mul_u32_u24_e32 v195, 0x110, v197
	v_add_u32_e32 v196, v196, v193
	v_add_u32_e32 v196, 0x8010, v196
	v_lshl_add_u32 v195, v191, 2, v195
	v_readfirstlane_b32 s92, v198
	v_add_u32_e32 v195, v195, v196
	v_lshl_add_u32 v196, v64, 2, v196
	v_add_lshl_u32 v199, v192, v64, 1
	s_waitcnt vmcnt(0)
	ds_write2_b32 v195, v164, v165 offset0:0 offset1:4
	ds_write2_b32 v195, v166, v167 offset0:8 offset1:12
	ds_write2_b32 v195, v168, v169 offset0:16 offset1:20
	ds_write2_b32 v195, v170, v171 offset0:24 offset1:28
	ds_write2_b32 v195, v172, v173 offset0:32 offset1:36
	ds_write2_b32 v195, v174, v175 offset0:40 offset1:44
	ds_write2_b32 v195, v176, v177 offset0:48 offset1:52
	ds_write2_b32 v195, v178, v179 offset0:56 offset1:60
	s_waitcnt lgkmcnt(0)
	ds_read_b32 v164, v196 offset:0
	ds_read_b32 v165, v196 offset:272
	ds_read_b32 v166, v196 offset:544
	ds_read_b32 v167, v196 offset:816
	ds_read_b32 v168, v196 offset:1088
	ds_read_b32 v169, v196 offset:1360
	ds_read_b32 v170, v196 offset:1632
	ds_read_b32 v171, v196 offset:1904
	ds_read_b32 v172, v196 offset:2176
	ds_read_b32 v173, v196 offset:2448
	ds_read_b32 v174, v196 offset:2720
	ds_read_b32 v175, v196 offset:2992
	ds_read_b32 v176, v196 offset:3264
	ds_read_b32 v177, v196 offset:3536
	ds_read_b32 v178, v196 offset:3808
	ds_read_b32 v179, v196 offset:4080
	s_add_i32 s93, s92, 0
	s_mov_b32 s94, s93
	s_mul_i32 s94, s94, 0x1600
	s_add_i32 s94, s94, 0x1a80000
	s_waitcnt lgkmcnt(15)
	v_cvt_pk_bf16_f32 v180, v164, v164
	v_add_u32_e32 v188, s94, v199
	global_store_short v188, v180, s[70:71]
	s_add_i32 s93, s92, 1
	s_mov_b32 s94, s93
	s_mul_i32 s94, s94, 0x1600
	s_add_i32 s94, s94, 0x1a80000
	s_waitcnt lgkmcnt(14)
	v_cvt_pk_bf16_f32 v181, v165, v165
	v_add_u32_e32 v189, s94, v199
	global_store_short v189, v181, s[70:71]
	s_add_i32 s93, s92, 2
	s_mov_b32 s94, s93
	s_mul_i32 s94, s94, 0x1600
	s_add_i32 s94, s94, 0x1a80000
	s_waitcnt lgkmcnt(13)
	v_cvt_pk_bf16_f32 v182, v166, v166
	v_add_u32_e32 v190, s94, v199
	global_store_short v190, v182, s[70:71]
	s_add_i32 s93, s92, 3
	s_mov_b32 s94, s93
	s_mul_i32 s94, s94, 0x1600
	s_add_i32 s94, s94, 0x1a80000
	s_waitcnt lgkmcnt(12)
	v_cvt_pk_bf16_f32 v183, v167, v167
	v_add_u32_e32 v191, s94, v199
	global_store_short v191, v183, s[70:71]
	s_add_i32 s93, s92, 4
	s_mov_b32 s94, s93
	s_mul_i32 s94, s94, 0x1600
	s_add_i32 s94, s94, 0x1a80000
	s_waitcnt lgkmcnt(11)
	v_cvt_pk_bf16_f32 v184, v168, v168
	v_add_u32_e32 v188, s94, v199
	global_store_short v188, v184, s[70:71]
	s_add_i32 s93, s92, 5
	s_mov_b32 s94, s93
	s_mul_i32 s94, s94, 0x1600
	s_add_i32 s94, s94, 0x1a80000
	s_waitcnt lgkmcnt(10)
; DI unsigned short f2bf(float x) { return (unsigned short)(pk2(x, 0.f) & 0xffffu); }
; DI void transpose_tile(unsigned char* smem, const int tid, const float* src, int K, int N, bf16_t* dst, int ldd, int permid, int kt, int nt) {
;     float (*tile)[65] = (float (*)[65])smem;
;     const int k0 = kt * 64, n0 = nt * 64;
;     float tv[16];
; #pragma unroll
;     for (int i = 0; i < 16; ++i) {
;         int kk = i * 4 + (tid >> 6), nn = tid & 63;
;         tv[i] = (n0 + nn < N) ? src[(size_t)(k0 + kk) * N + n0 + nn] : 0.f;
;     }
; #pragma unroll
;     for (int i = 0; i < 16; ++i) tile[tid & 63][i * 4 + (tid >> 6)] = tv[i];
;     __syncthreads();
; #pragma unroll 4
;     for (int i = 0; i < 16; ++i) {
;         int nn = i * 4 + (tid >> 6), kk = tid & 63;
;         int n = n0 + nn;
;         if (n < N) {
;             int row = n;
;             if (permid == 1) row = (n < 2048) ? n : ((n >= 2056) ? n - 8 : -1);
;             else if (permid == 2) row = (n < 1024) ? ((n >> 2) * 8 + (n & 3)) : (((n - 1024) >> 2) * 8 + 4 + (n & 3));
;             else if (permid == 3) row = (n < 2816) ? ((n >> 2) * 8 + (n & 3)) : (((n - 2816) >> 2) * 8 + 4 + (n & 3));
;             if (row >= 0) dst[(size_t)row * ldd + k0 + kk] = f2bf(tile[nn][kk]);
;         }
;     }
;     __syncthreads();
; DI void phase0(const Params& p, unsigned char* smem, const int tid, const int vb, const int nvb) {
;     ...
;             if (id < 1408) { transpose_tile(smem, tid, p.in[24], 1024, 5632, (bf16_t*)(ws + OFF_WUP), 1024, 3, id / 88, id % 88); continue; }
	v_cvt_pk_bf16_f32 v185, v169, v169
	v_add_u32_e32 v189, s94, v199
	global_store_short v189, v185, s[70:71]
	s_add_i32 s93, s92, 6
	s_mov_b32 s94, s93
	s_mul_i32 s94, s94, 0x1600
	s_add_i32 s94, s94, 0x1a80000
	s_waitcnt lgkmcnt(9)
	v_cvt_pk_bf16_f32 v186, v170, v170
	v_add_u32_e32 v190, s94, v199
	global_store_short v190, v186, s[70:71]
	s_add_i32 s93, s92, 7
	s_mov_b32 s94, s93
	s_mul_i32 s94, s94, 0x1600
	s_add_i32 s94, s94, 0x1a80000
	s_waitcnt lgkmcnt(8)
	v_cvt_pk_bf16_f32 v187, v171, v171
	v_add_u32_e32 v191, s94, v199
	global_store_short v191, v187, s[70:71]
	s_add_i32 s93, s92, 8
	s_mov_b32 s94, s93
	s_mul_i32 s94, s94, 0x1600
	s_add_i32 s94, s94, 0x1a80000
	s_waitcnt lgkmcnt(7)
	v_cvt_pk_bf16_f32 v180, v172, v172
	v_add_u32_e32 v188, s94, v199
	global_store_short v188, v180, s[70:71]
	s_add_i32 s93, s92, 9
	s_mov_b32 s94, s93
	s_mul_i32 s94, s94, 0x1600
	s_add_i32 s94, s94, 0x1a80000
	s_waitcnt lgkmcnt(6)
	v_cvt_pk_bf16_f32 v181, v173, v173
	v_add_u32_e32 v189, s94, v199
	global_store_short v189, v181, s[70:71]
	s_add_i32 s93, s92, 10
	s_mov_b32 s94, s93
	s_mul_i32 s94, s94, 0x1600
	s_add_i32 s94, s94, 0x1a80000
	s_waitcnt lgkmcnt(5)
	v_cvt_pk_bf16_f32 v182, v174, v174
	v_add_u32_e32 v190, s94, v199
	global_store_short v190, v182, s[70:71]
	s_add_i32 s93, s92, 11
	s_mov_b32 s94, s93
	s_mul_i32 s94, s94, 0x1600
	s_add_i32 s94, s94, 0x1a80000
	s_waitcnt lgkmcnt(4)
	v_cvt_pk_bf16_f32 v183, v175, v175
	v_add_u32_e32 v191, s94, v199
	global_store_short v191, v183, s[70:71]
	s_add_i32 s93, s92, 12
	s_mov_b32 s94, s93
	s_mul_i32 s94, s94, 0x1600
	s_add_i32 s94, s94, 0x1a80000
	s_waitcnt lgkmcnt(3)
	v_cvt_pk_bf16_f32 v184, v176, v176
	v_add_u32_e32 v188, s94, v199
	global_store_short v188, v184, s[70:71]
	s_add_i32 s93, s92, 13
	s_mov_b32 s94, s93
	s_mul_i32 s94, s94, 0x1600
	s_add_i32 s94, s94, 0x1a80000
	s_waitcnt lgkmcnt(2)
	v_cvt_pk_bf16_f32 v185, v177, v177
	v_add_u32_e32 v189, s94, v199
	global_store_short v189, v185, s[70:71]
	s_add_i32 s93, s92, 14
	s_mov_b32 s94, s93
	s_mul_i32 s94, s94, 0x1600
	s_add_i32 s94, s94, 0x1a80000
	s_waitcnt lgkmcnt(1)
	v_cvt_pk_bf16_f32 v186, v178, v178
	v_add_u32_e32 v190, s94, v199
	global_store_short v190, v186, s[70:71]
	s_add_i32 s93, s92, 15
	s_mov_b32 s94, s93
	s_mul_i32 s94, s94, 0x1600
	s_add_i32 s94, s94, 0x1a80000
	s_waitcnt lgkmcnt(0)
	v_cvt_pk_bf16_f32 v187, v179, v179
	v_add_u32_e32 v191, s94, v199
	global_store_short v191, v187, s[70:71]
.LBB0_48:
	s_andn2_saveexec_b64 s[36:37], s[4:5]
	s_cbranch_execz .LBB0_60
	v_add_u32_e32 v190, 0xfffff830, v4
	v_mul_u32_u24_e32 v188, 0x2e9, v190
	v_lshrrev_b32_e32 v188, 16, v188
	v_mul_u32_u24_e32 v189, 0x58, v188
	v_sub_u32_e32 v189, v190, v189
	v_lshlrev_b32_e32 v190, 6, v189
	v_lshlrev_b32_e32 v192, 6, v188
	v_lshrrev_b32_e32 v191, 4, v64
	v_and_b32_e32 v197, 15, v64
	v_lshl_add_u32 v198, v66, 4, v190
	v_add_u32_e32 v199, v192, v191
	v_mul_u32_u24_e32 v193, 0x1600, v199
	v_lshlrev_b32_e32 v196, 6, v191
	v_add_lshl_u32 v193, v193, v198, 2
	v_sub_u32_e32 v193, v193, v196
	v_add_co_u32_e32 v194, vcc, v86, v193
	s_mov_b64 s[88:89], 0x16000
	s_nop 0
	v_addc_co_u32_e32 v195, vcc, 0, v87, vcc
	global_load_dword v164, v[194:195], off
	v_lshl_add_u64 v[194:195], v[194:195], 0, s[88:89]
	global_load_dword v165, v[194:195], off
	v_lshl_add_u64 v[194:195], v[194:195], 0, s[88:89]
	global_load_dword v166, v[194:195], off
	v_lshl_add_u64 v[194:195], v[194:195], 0, s[88:89]
	global_load_dword v167, v[194:195], off
	v_lshl_add_u64 v[194:195], v[194:195], 0, s[88:89]
	global_load_dword v168, v[194:195], off
	v_lshl_add_u64 v[194:195], v[194:195], 0, s[88:89]
	global_load_dword v169, v[194:195], off
	v_lshl_add_u64 v[194:195], v[194:195], 0, s[88:89]
	global_load_dword v170, v[194:195], off
	v_lshl_add_u64 v[194:195], v[194:195], 0, s[88:89]
	global_load_dword v171, v[194:195], off
	v_lshl_add_u64 v[194:195], v[194:195], 0, s[88:89]
	global_load_dword v172, v[194:195], off
	v_lshl_add_u64 v[194:195], v[194:195], 0, s[88:89]
	global_load_dword v173, v[194:195], off
	v_lshl_add_u64 v[194:195], v[194:195], 0, s[88:89]
	global_load_dword v174, v[194:195], off
	v_lshl_add_u64 v[194:195], v[194:195], 0, s[88:89]
	global_load_dword v175, v[194:195], off
	v_lshl_add_u64 v[194:195], v[194:195], 0, s[88:89]
	global_load_dword v176, v[194:195], off
	v_lshl_add_u64 v[194:195], v[194:195], 0, s[88:89]
	global_load_dword v177, v[194:195], off
	v_lshl_add_u64 v[194:195], v[194:195], 0, s[88:89]
	global_load_dword v178, v[194:195], off
	v_lshl_add_u64 v[194:195], v[194:195], 0, s[88:89]
	global_load_dword v179, v[194:195], off
	v_lshrrev_b32_e32 v196, 8, v250
	v_mul_u32_u24_e32 v193, 0x1100, v66
	v_lshlrev_b32_e32 v196, 16, v196
	v_mul_u32_u24_e32 v195, 0x110, v197
	v_add_u32_e32 v196, v196, v193
	v_add_u32_e32 v196, 0x8010, v196
	v_lshl_add_u32 v195, v191, 2, v195
	v_readfirstlane_b32 s92, v198
	v_add_u32_e32 v195, v195, v196
	v_lshl_add_u32 v196, v64, 2, v196
	v_add_lshl_u32 v199, v192, v64, 1
	s_waitcnt vmcnt(0)
	ds_write2_b32 v195, v164, v165 offset0:0 offset1:4
	ds_write2_b32 v195, v166, v167 offset0:8 offset1:12
	ds_write2_b32 v195, v168, v169 offset0:16 offset1:20
	ds_write2_b32 v195, v170, v171 offset0:24 offset1:28
	ds_write2_b32 v195, v172, v173 offset0:32 offset1:36
	ds_write2_b32 v195, v174, v175 offset0:40 offset1:44
	ds_write2_b32 v195, v176, v177 offset0:48 offset1:52
	ds_write2_b32 v195, v178, v179 offset0:56 offset1:60
	s_waitcnt lgkmcnt(0)
; DI unsigned short f2bf(float x) { return (unsigned short)(pk2(x, 0.f) & 0xffffu); }
; DI void transpose_tile(unsigned char* smem, const int tid, const float* src, int K, int N, bf16_t* dst, int ldd, int permid, int kt, int nt) {
;     ...
; #pragma unroll 4
;     for (int i = 0; i < 16; ++i) {
;         int nn = i * 4 + (tid >> 6), kk = tid & 63;
;         int n = n0 + nn;
;         if (n < N) {
;             int row = n;
;             if (permid == 1) row = (n < 2048) ? n : ((n >= 2056) ? n - 8 : -1);
;             else if (permid == 2) row = (n < 1024) ? ((n >> 2) * 8 + (n & 3)) : (((n - 1024) >> 2) * 8 + 4 + (n & 3));
;             else if (permid == 3) row = (n < 2816) ? ((n >> 2) * 8 + (n & 3)) : (((n - 2816) >> 2) * 8 + 4 + (n & 3));
;             if (row >= 0) dst[(size_t)row * ldd + k0 + kk] = f2bf(tile[nn][kk]);
	ds_read_b32 v164, v196 offset:0
	ds_read_b32 v165, v196 offset:272
	ds_read_b32 v166, v196 offset:544
	ds_read_b32 v167, v196 offset:816
	ds_read_b32 v168, v196 offset:1088
	ds_read_b32 v169, v196 offset:1360
	ds_read_b32 v170, v196 offset:1632
	ds_read_b32 v171, v196 offset:1904
	ds_read_b32 v172, v196 offset:2176
	ds_read_b32 v173, v196 offset:2448
	ds_read_b32 v174, v196 offset:2720
	ds_read_b32 v175, v196 offset:2992
	ds_read_b32 v176, v196 offset:3264
	ds_read_b32 v177, v196 offset:3536
	ds_read_b32 v178, v196 offset:3808
	ds_read_b32 v179, v196 offset:4080
	s_add_i32 s93, s92, 0
	s_cmpk_lt_u32 s93, 0xb00
	s_cselect_b32 s95, 0, 0xb00
	s_cselect_b32 s96, 0, 4
	s_sub_i32 s95, s93, s95
	s_lshr_b32 s94, s95, 2
	s_and_b32 s95, s95, 3
	s_lshl_b32 s94, s94, 3
	s_add_i32 s94, s94, s95
	s_add_i32 s94, s94, s96
	s_mul_i32 s94, s94, 0x800
	s_add_i32 s94, s94, 0xf80000
	s_waitcnt lgkmcnt(15)
	v_cvt_pk_bf16_f32 v180, v164, v164
	v_add_u32_e32 v188, s94, v199
	global_store_short v188, v180, s[70:71]
	s_add_i32 s93, s92, 1
	s_cmpk_lt_u32 s93, 0xb00
	s_cselect_b32 s95, 0, 0xb00
	s_cselect_b32 s96, 0, 4
	s_sub_i32 s95, s93, s95
	s_lshr_b32 s94, s95, 2
	s_and_b32 s95, s95, 3
	s_lshl_b32 s94, s94, 3
	s_add_i32 s94, s94, s95
	s_add_i32 s94, s94, s96
	s_mul_i32 s94, s94, 0x800
	s_add_i32 s94, s94, 0xf80000
	s_waitcnt lgkmcnt(14)
	v_cvt_pk_bf16_f32 v181, v165, v165
	v_add_u32_e32 v189, s94, v199
	global_store_short v189, v181, s[70:71]
	s_add_i32 s93, s92, 2
	s_cmpk_lt_u32 s93, 0xb00
	s_cselect_b32 s95, 0, 0xb00
	s_cselect_b32 s96, 0, 4
	s_sub_i32 s95, s93, s95
	s_lshr_b32 s94, s95, 2
	s_and_b32 s95, s95, 3
	s_lshl_b32 s94, s94, 3
	s_add_i32 s94, s94, s95
	s_add_i32 s94, s94, s96
	s_mul_i32 s94, s94, 0x800
	s_add_i32 s94, s94, 0xf80000
	s_waitcnt lgkmcnt(13)
	v_cvt_pk_bf16_f32 v182, v166, v166
	v_add_u32_e32 v190, s94, v199
	global_store_short v190, v182, s[70:71]
	s_add_i32 s93, s92, 3
	s_cmpk_lt_u32 s93, 0xb00
	s_cselect_b32 s95, 0, 0xb00
	s_cselect_b32 s96, 0, 4
	s_sub_i32 s95, s93, s95
	s_lshr_b32 s94, s95, 2
	s_and_b32 s95, s95, 3
	s_lshl_b32 s94, s94, 3
	s_add_i32 s94, s94, s95
	s_add_i32 s94, s94, s96
	s_mul_i32 s94, s94, 0x800
	s_add_i32 s94, s94, 0xf80000
	s_waitcnt lgkmcnt(12)
	v_cvt_pk_bf16_f32 v183, v167, v167
	v_add_u32_e32 v191, s94, v199
	global_store_short v191, v183, s[70:71]
	s_add_i32 s93, s92, 4
	s_cmpk_lt_u32 s93, 0xb00
	s_cselect_b32 s95, 0, 0xb00
	s_cselect_b32 s96, 0, 4
	s_sub_i32 s95, s93, s95
	s_lshr_b32 s94, s95, 2
	s_and_b32 s95, s95, 3
	s_lshl_b32 s94, s94, 3
	s_add_i32 s94, s94, s95
	s_add_i32 s94, s94, s96
	s_mul_i32 s94, s94, 0x800
	s_add_i32 s94, s94, 0xf80000
	s_waitcnt lgkmcnt(11)
	v_cvt_pk_bf16_f32 v184, v168, v168
	v_add_u32_e32 v188, s94, v199
	global_store_short v188, v184, s[70:71]
	s_add_i32 s93, s92, 5
	s_cmpk_lt_u32 s93, 0xb00
	s_cselect_b32 s95, 0, 0xb00
	s_cselect_b32 s96, 0, 4
	s_sub_i32 s95, s93, s95
	s_lshr_b32 s94, s95, 2
	s_and_b32 s95, s95, 3
	s_lshl_b32 s94, s94, 3
	s_add_i32 s94, s94, s95
	s_add_i32 s94, s94, s96
	s_mul_i32 s94, s94, 0x800
	s_add_i32 s94, s94, 0xf80000
	s_waitcnt lgkmcnt(10)
	v_cvt_pk_bf16_f32 v185, v169, v169
	v_add_u32_e32 v189, s94, v199
	global_store_short v189, v185, s[70:71]
	s_add_i32 s93, s92, 6
	s_cmpk_lt_u32 s93, 0xb00
	s_cselect_b32 s95, 0, 0xb00
	s_cselect_b32 s96, 0, 4
	s_sub_i32 s95, s93, s95
	s_lshr_b32 s94, s95, 2
	s_and_b32 s95, s95, 3
	s_lshl_b32 s94, s94, 3
	s_add_i32 s94, s94, s95
	s_add_i32 s94, s94, s96
	s_mul_i32 s94, s94, 0x800
	s_add_i32 s94, s94, 0xf80000
	s_waitcnt lgkmcnt(9)
	v_cvt_pk_bf16_f32 v186, v170, v170
	v_add_u32_e32 v190, s94, v199
	global_store_short v190, v186, s[70:71]
	s_add_i32 s93, s92, 7
	s_cmpk_lt_u32 s93, 0xb00
	s_cselect_b32 s95, 0, 0xb00
	s_cselect_b32 s96, 0, 4
	s_sub_i32 s95, s93, s95
	s_lshr_b32 s94, s95, 2
	s_and_b32 s95, s95, 3
	s_lshl_b32 s94, s94, 3
	s_add_i32 s94, s94, s95
	s_add_i32 s94, s94, s96
	s_mul_i32 s94, s94, 0x800
	s_add_i32 s94, s94, 0xf80000
	s_waitcnt lgkmcnt(8)
; DI unsigned short f2bf(float x) { return (unsigned short)(pk2(x, 0.f) & 0xffffu); }
; DI void transpose_tile(unsigned char* smem, const int tid, const float* src, int K, int N, bf16_t* dst, int ldd, int permid, int kt, int nt) {
;     ...
; #pragma unroll 4
;     for (int i = 0; i < 16; ++i) {
;         int nn = i * 4 + (tid >> 6), kk = tid & 63;
;         int n = n0 + nn;
;         if (n < N) {
;             int row = n;
;             if (permid == 1) row = (n < 2048) ? n : ((n >= 2056) ? n - 8 : -1);
;             else if (permid == 2) row = (n < 1024) ? ((n >> 2) * 8 + (n & 3)) : (((n - 1024) >> 2) * 8 + 4 + (n & 3));
;             else if (permid == 3) row = (n < 2816) ? ((n >> 2) * 8 + (n & 3)) : (((n - 2816) >> 2) * 8 + 4 + (n & 3));
;             if (row >= 0) dst[(size_t)row * ldd + k0 + kk] = f2bf(tile[nn][kk]);
	v_cvt_pk_bf16_f32 v187, v171, v171
	v_add_u32_e32 v191, s94, v199
	global_store_short v191, v187, s[70:71]
	s_add_i32 s93, s92, 8
	s_cmpk_lt_u32 s93, 0xb00
	s_cselect_b32 s95, 0, 0xb00
	s_cselect_b32 s96, 0, 4
	s_sub_i32 s95, s93, s95
	s_lshr_b32 s94, s95, 2
	s_and_b32 s95, s95, 3
	s_lshl_b32 s94, s94, 3
	s_add_i32 s94, s94, s95
	s_add_i32 s94, s94, s96
	s_mul_i32 s94, s94, 0x800
	s_add_i32 s94, s94, 0xf80000
	s_waitcnt lgkmcnt(7)
	v_cvt_pk_bf16_f32 v180, v172, v172
	v_add_u32_e32 v188, s94, v199
	global_store_short v188, v180, s[70:71]
	s_add_i32 s93, s92, 9
	s_cmpk_lt_u32 s93, 0xb00
	s_cselect_b32 s95, 0, 0xb00
	s_cselect_b32 s96, 0, 4
	s_sub_i32 s95, s93, s95
	s_lshr_b32 s94, s95, 2
	s_and_b32 s95, s95, 3
	s_lshl_b32 s94, s94, 3
	s_add_i32 s94, s94, s95
	s_add_i32 s94, s94, s96
	s_mul_i32 s94, s94, 0x800
	s_add_i32 s94, s94, 0xf80000
	s_waitcnt lgkmcnt(6)
	v_cvt_pk_bf16_f32 v181, v173, v173
	v_add_u32_e32 v189, s94, v199
	global_store_short v189, v181, s[70:71]
	s_add_i32 s93, s92, 10
	s_cmpk_lt_u32 s93, 0xb00
	s_cselect_b32 s95, 0, 0xb00
	s_cselect_b32 s96, 0, 4
	s_sub_i32 s95, s93, s95
	s_lshr_b32 s94, s95, 2
	s_and_b32 s95, s95, 3
	s_lshl_b32 s94, s94, 3
	s_add_i32 s94, s94, s95
	s_add_i32 s94, s94, s96
	s_mul_i32 s94, s94, 0x800
	s_add_i32 s94, s94, 0xf80000
	s_waitcnt lgkmcnt(5)
	v_cvt_pk_bf16_f32 v182, v174, v174
	v_add_u32_e32 v190, s94, v199
	global_store_short v190, v182, s[70:71]
	s_add_i32 s93, s92, 11
	s_cmpk_lt_u32 s93, 0xb00
	s_cselect_b32 s95, 0, 0xb00
	s_cselect_b32 s96, 0, 4
	s_sub_i32 s95, s93, s95
	s_lshr_b32 s94, s95, 2
	s_and_b32 s95, s95, 3
	s_lshl_b32 s94, s94, 3
	s_add_i32 s94, s94, s95
	s_add_i32 s94, s94, s96
	s_mul_i32 s94, s94, 0x800
	s_add_i32 s94, s94, 0xf80000
	s_waitcnt lgkmcnt(4)
	v_cvt_pk_bf16_f32 v183, v175, v175
	v_add_u32_e32 v191, s94, v199
	global_store_short v191, v183, s[70:71]
	s_add_i32 s93, s92, 12
	s_cmpk_lt_u32 s93, 0xb00
	s_cselect_b32 s95, 0, 0xb00
	s_cselect_b32 s96, 0, 4
	s_sub_i32 s95, s93, s95
	s_lshr_b32 s94, s95, 2
	s_and_b32 s95, s95, 3
	s_lshl_b32 s94, s94, 3
	s_add_i32 s94, s94, s95
	s_add_i32 s94, s94, s96
	s_mul_i32 s94, s94, 0x800
	s_add_i32 s94, s94, 0xf80000
	s_waitcnt lgkmcnt(3)
	v_cvt_pk_bf16_f32 v184, v176, v176
	v_add_u32_e32 v188, s94, v199
	global_store_short v188, v184, s[70:71]
	s_add_i32 s93, s92, 13
	s_cmpk_lt_u32 s93, 0xb00
	s_cselect_b32 s95, 0, 0xb00
	s_cselect_b32 s96, 0, 4
	s_sub_i32 s95, s93, s95
	s_lshr_b32 s94, s95, 2
	s_and_b32 s95, s95, 3
	s_lshl_b32 s94, s94, 3
	s_add_i32 s94, s94, s95
	s_add_i32 s94, s94, s96
	s_mul_i32 s94, s94, 0x800
	s_add_i32 s94, s94, 0xf80000
	s_waitcnt lgkmcnt(2)
	v_cvt_pk_bf16_f32 v185, v177, v177
	v_add_u32_e32 v189, s94, v199
	global_store_short v189, v185, s[70:71]
	s_add_i32 s93, s92, 14
	s_cmpk_lt_u32 s93, 0xb00
	s_cselect_b32 s95, 0, 0xb00
	s_cselect_b32 s96, 0, 4
	s_sub_i32 s95, s93, s95
	s_lshr_b32 s94, s95, 2
	s_and_b32 s95, s95, 3
	s_lshl_b32 s94, s94, 3
	s_add_i32 s94, s94, s95
	s_add_i32 s94, s94, s96
	s_mul_i32 s94, s94, 0x800
	s_add_i32 s94, s94, 0xf80000
	s_waitcnt lgkmcnt(1)
	v_cvt_pk_bf16_f32 v186, v178, v178
	v_add_u32_e32 v190, s94, v199
	global_store_short v190, v186, s[70:71]
	s_add_i32 s93, s92, 15
	s_cmpk_lt_u32 s93, 0xb00
	s_cselect_b32 s95, 0, 0xb00
	s_cselect_b32 s96, 0, 4
	s_sub_i32 s95, s93, s95
	s_lshr_b32 s94, s95, 2
	s_and_b32 s95, s95, 3
	s_lshl_b32 s94, s94, 3
	s_add_i32 s94, s94, s95
	s_add_i32 s94, s94, s96
	s_mul_i32 s94, s94, 0x800
	s_add_i32 s94, s94, 0xf80000
	s_waitcnt lgkmcnt(0)
	v_cvt_pk_bf16_f32 v187, v179, v179
	v_add_u32_e32 v191, s94, v199
	global_store_short v191, v187, s[70:71]

; DI unsigned short f2bf(float x) { return (unsigned short)(pk2(x, 0.f) & 0xffffu); }
; DI void transpose_tile(unsigned char* smem, const int tid, const float* src, int K, int N, bf16_t* dst, int ldd, int permid, int kt, int nt) {
;     float (*tile)[65] = (float (*)[65])smem;
;     const int k0 = kt * 64, n0 = nt * 64;
;     float tv[16];
; #pragma unroll
;     for (int i = 0; i < 16; ++i) {
;         int kk = i * 4 + (tid >> 6), nn = tid & 63;
;         tv[i] = (n0 + nn < N) ? src[(size_t)(k0 + kk) * N + n0 + nn] : 0.f;
;     }
; #pragma unroll
;     for (int i = 0; i < 16; ++i) tile[tid & 63][i * 4 + (tid >> 6)] = tv[i];
;     __syncthreads();
; #pragma unroll 4
;     for (int i = 0; i < 16; ++i) {
;         int nn = i * 4 + (tid >> 6), kk = tid & 63;
;         int n = n0 + nn;
;         if (n < N) {
;             int row = n;
;             if (permid == 1) row = (n < 2048) ? n : ((n >= 2056) ? n - 8 : -1);
;             else if (permid == 2) row = (n < 1024) ? ((n >> 2) * 8 + (n & 3)) : (((n - 1024) >> 2) * 8 + 4 + (n & 3));
;             else if (permid == 3) row = (n < 2816) ? ((n >> 2) * 8 + (n & 3)) : (((n - 2816) >> 2) * 8 + 4 + (n & 3));
;             if (row >= 0) dst[(size_t)row * ldd + k0 + kk] = f2bf(tile[nn][kk]);
;         }
;     }
;     __syncthreads();
; DI void phase0(const Params& p, unsigned char* smem, const int tid, const int vb, const int nvb) {
;     ...
;             if (id < 1168) { transpose_tile(smem, tid, p.in[4], 1024, 4616, (bf16_t*)(ws + OFF_WIN), 1024, 1, id / 73, id % 73); continue; }
.LBB0_89:
	s_andn2_saveexec_b64 s[24:25], s[24:25]
	s_cbranch_execz .LBB0_20
	v_mul_u32_u24_e32 v188, 0x382, v4
	v_lshrrev_b32_e32 v188, 16, v188
	v_mul_u32_u24_e32 v189, 0x49, v188
	v_sub_u32_e32 v189, v4, v189
	v_lshlrev_b32_e32 v190, 6, v189
	v_lshlrev_b32_e32 v192, 6, v188
	v_lshrrev_b32_e32 v191, 4, v64
	v_and_b32_e32 v197, 15, v64
	v_lshl_add_u32 v198, v66, 4, v190
	v_add_u32_e32 v199, v192, v191
	v_mul_u32_u24_e32 v193, 0x1208, v199
	v_lshlrev_b32_e32 v196, 6, v191
	v_add_lshl_u32 v193, v193, v198, 2
	v_sub_u32_e32 v193, v193, v196
	v_add_co_u32_e32 v194, vcc, v94, v193
	s_mov_b64 s[88:89], 0x12080
	s_nop 0
	v_addc_co_u32_e32 v195, vcc, 0, v95, vcc
	v_add_u32_e32 v193, v198, v197
	s_movk_i32 s92, 0x1208
	v_cmp_gt_u32_e32 vcc, s92, v193
	s_and_saveexec_b64 s[96:97], vcc
	global_load_dword v164, v[194:195], off
	v_lshl_add_u64 v[194:195], v[194:195], 0, s[88:89]
	global_load_dword v165, v[194:195], off
	v_lshl_add_u64 v[194:195], v[194:195], 0, s[88:89]
	global_load_dword v166, v[194:195], off
	v_lshl_add_u64 v[194:195], v[194:195], 0, s[88:89]
	global_load_dword v167, v[194:195], off
	v_lshl_add_u64 v[194:195], v[194:195], 0, s[88:89]
	global_load_dword v168, v[194:195], off
	v_lshl_add_u64 v[194:195], v[194:195], 0, s[88:89]
	global_load_dword v169, v[194:195], off
	v_lshl_add_u64 v[194:195], v[194:195], 0, s[88:89]
	global_load_dword v170, v[194:195], off
	v_lshl_add_u64 v[194:195], v[194:195], 0, s[88:89]
	global_load_dword v171, v[194:195], off
	v_lshl_add_u64 v[194:195], v[194:195], 0, s[88:89]
	global_load_dword v172, v[194:195], off
	v_lshl_add_u64 v[194:195], v[194:195], 0, s[88:89]
	global_load_dword v173, v[194:195], off
	v_lshl_add_u64 v[194:195], v[194:195], 0, s[88:89]
	global_load_dword v174, v[194:195], off
	v_lshl_add_u64 v[194:195], v[194:195], 0, s[88:89]
	global_load_dword v175, v[194:195], off
	v_lshl_add_u64 v[194:195], v[194:195], 0, s[88:89]
	global_load_dword v176, v[194:195], off
	v_lshl_add_u64 v[194:195], v[194:195], 0, s[88:89]
	global_load_dword v177, v[194:195], off
	v_lshl_add_u64 v[194:195], v[194:195], 0, s[88:89]
	global_load_dword v178, v[194:195], off
	v_lshl_add_u64 v[194:195], v[194:195], 0, s[88:89]
	global_load_dword v179, v[194:195], off
	s_or_b64 exec, exec, s[96:97]
	v_lshrrev_b32_e32 v196, 8, v250
	v_mul_u32_u24_e32 v193, 0x1100, v66
	v_lshlrev_b32_e32 v196, 16, v196
	v_mul_u32_u24_e32 v195, 0x110, v197
	v_add_u32_e32 v196, v196, v193
	v_add_u32_e32 v196, 0x8010, v196
	v_lshl_add_u32 v195, v191, 2, v195
	v_readfirstlane_b32 s92, v198
	v_add_u32_e32 v195, v195, v196
	v_lshl_add_u32 v196, v64, 2, v196
	v_add_lshl_u32 v199, v192, v64, 1
	s_waitcnt vmcnt(0)
	ds_write2_b32 v195, v164, v165 offset0:0 offset1:4
	ds_write2_b32 v195, v166, v167 offset0:8 offset1:12
	ds_write2_b32 v195, v168, v169 offset0:16 offset1:20
	ds_write2_b32 v195, v170, v171 offset0:24 offset1:28
	ds_write2_b32 v195, v172, v173 offset0:32 offset1:36
	ds_write2_b32 v195, v174, v175 offset0:40 offset1:44
	ds_write2_b32 v195, v176, v177 offset0:48 offset1:52
	ds_write2_b32 v195, v178, v179 offset0:56 offset1:60
	s_waitcnt lgkmcnt(0)
	ds_read_b32 v164, v196 offset:0
	ds_read_b32 v165, v196 offset:272
	ds_read_b32 v166, v196 offset:544
	ds_read_b32 v167, v196 offset:816
	ds_read_b32 v168, v196 offset:1088
	ds_read_b32 v169, v196 offset:1360
	ds_read_b32 v170, v196 offset:1632
	ds_read_b32 v171, v196 offset:1904
	ds_read_b32 v172, v196 offset:2176
	ds_read_b32 v173, v196 offset:2448
	ds_read_b32 v174, v196 offset:2720
	ds_read_b32 v175, v196 offset:2992
	ds_read_b32 v176, v196 offset:3264
	ds_read_b32 v177, v196 offset:3536
	ds_read_b32 v178, v196 offset:3808
	ds_read_b32 v179, v196 offset:4080
	s_add_i32 s93, s92, 0
	s_cmpk_ge_u32 s93, 0x1208
	s_cbranch_scc1 .Lp0t_in_0
	s_add_i32 s94, s93, 0xfffff800
	s_cmp_lt_u32 s94, 8
	s_cbranch_scc1 .Lp0t_in_0
	s_add_i32 s94, s93, -8
	s_cmpk_lt_u32 s93, 0x800
	s_cselect_b32 s94, s93, s94
	s_mul_i32 s94, s94, 0x800
	s_waitcnt lgkmcnt(15)
	v_cvt_pk_bf16_f32 v180, v164, v164
	v_add_u32_e32 v188, s94, v199
	global_store_short v188, v180, s[70:71]
.Lp0t_in_0:
	s_add_i32 s93, s92, 1
	s_cmpk_ge_u32 s93, 0x1208
	s_cbranch_scc1 .Lp0t_in_1
	s_add_i32 s94, s93, 0xfffff800
	s_cmp_lt_u32 s94, 8
	s_cbranch_scc1 .Lp0t_in_1
	s_add_i32 s94, s93, -8
	s_cmpk_lt_u32 s93, 0x800
	s_cselect_b32 s94, s93, s94
	s_mul_i32 s94, s94, 0x800
	s_waitcnt lgkmcnt(14)
	v_cvt_pk_bf16_f32 v181, v165, v165
	v_add_u32_e32 v189, s94, v199
	global_store_short v189, v181, s[70:71]
.Lp0t_in_1:
	s_add_i32 s93, s92, 2
	s_cmpk_ge_u32 s93, 0x1208
	s_cbranch_scc1 .Lp0t_in_2
	s_add_i32 s94, s93, 0xfffff800
	s_cmp_lt_u32 s94, 8
	s_cbranch_scc1 .Lp0t_in_2
	s_add_i32 s94, s93, -8
	s_cmpk_lt_u32 s93, 0x800
	s_cselect_b32 s94, s93, s94
	s_mul_i32 s94, s94, 0x800
	s_waitcnt lgkmcnt(13)
	v_cvt_pk_bf16_f32 v182, v166, v166
	v_add_u32_e32 v190, s94, v199
	global_store_short v190, v182, s[70:71]
.Lp0t_in_2:
	s_add_i32 s93, s92, 3
	s_cmpk_ge_u32 s93, 0x1208
	s_cbranch_scc1 .Lp0t_in_3
	s_add_i32 s94, s93, 0xfffff800
	s_cmp_lt_u32 s94, 8
	s_cbranch_scc1 .Lp0t_in_3
	s_add_i32 s94, s93, -8
	s_cmpk_lt_u32 s93, 0x800
	s_cselect_b32 s94, s93, s94
	s_mul_i32 s94, s94, 0x800
	s_waitcnt lgkmcnt(12)
	v_cvt_pk_bf16_f32 v183, v167, v167
	v_add_u32_e32 v191, s94, v199
	global_store_short v191, v183, s[70:71]
; DI unsigned short f2bf(float x) { return (unsigned short)(pk2(x, 0.f) & 0xffffu); }
; DI void transpose_tile(unsigned char* smem, const int tid, const float* src, int K, int N, bf16_t* dst, int ldd, int permid, int kt, int nt) {
;     ...
; #pragma unroll 4
;     for (int i = 0; i < 16; ++i) {
;         int nn = i * 4 + (tid >> 6), kk = tid & 63;
;         int n = n0 + nn;
;         if (n < N) {
;             int row = n;
;             if (permid == 1) row = (n < 2048) ? n : ((n >= 2056) ? n - 8 : -1);
;             else if (permid == 2) row = (n < 1024) ? ((n >> 2) * 8 + (n & 3)) : (((n - 1024) >> 2) * 8 + 4 + (n & 3));
;             else if (permid == 3) row = (n < 2816) ? ((n >> 2) * 8 + (n & 3)) : (((n - 2816) >> 2) * 8 + 4 + (n & 3));
;             if (row >= 0) dst[(size_t)row * ldd + k0 + kk] = f2bf(tile[nn][kk]);
;         }
;     }
;     __syncthreads();
.Lp0t_in_3:
	s_add_i32 s93, s92, 4
	s_cmpk_ge_u32 s93, 0x1208
	s_cbranch_scc1 .Lp0t_in_4
	s_add_i32 s94, s93, 0xfffff800
	s_cmp_lt_u32 s94, 8
	s_cbranch_scc1 .Lp0t_in_4
	s_add_i32 s94, s93, -8
	s_cmpk_lt_u32 s93, 0x800
	s_cselect_b32 s94, s93, s94
	s_mul_i32 s94, s94, 0x800
	s_waitcnt lgkmcnt(11)
	v_cvt_pk_bf16_f32 v184, v168, v168
	v_add_u32_e32 v188, s94, v199
	global_store_short v188, v184, s[70:71]
.Lp0t_in_4:
	s_add_i32 s93, s92, 5
	s_cmpk_ge_u32 s93, 0x1208
	s_cbranch_scc1 .Lp0t_in_5
	s_add_i32 s94, s93, 0xfffff800
	s_cmp_lt_u32 s94, 8
	s_cbranch_scc1 .Lp0t_in_5
	s_add_i32 s94, s93, -8
	s_cmpk_lt_u32 s93, 0x800
	s_cselect_b32 s94, s93, s94
	s_mul_i32 s94, s94, 0x800
	s_waitcnt lgkmcnt(10)
	v_cvt_pk_bf16_f32 v185, v169, v169
	v_add_u32_e32 v189, s94, v199
	global_store_short v189, v185, s[70:71]
.Lp0t_in_5:
	s_add_i32 s93, s92, 6
	s_cmpk_ge_u32 s93, 0x1208
	s_cbranch_scc1 .Lp0t_in_6
	s_add_i32 s94, s93, 0xfffff800
	s_cmp_lt_u32 s94, 8
	s_cbranch_scc1 .Lp0t_in_6
	s_add_i32 s94, s93, -8
	s_cmpk_lt_u32 s93, 0x800
	s_cselect_b32 s94, s93, s94
	s_mul_i32 s94, s94, 0x800
	s_waitcnt lgkmcnt(9)
	v_cvt_pk_bf16_f32 v186, v170, v170
	v_add_u32_e32 v190, s94, v199
	global_store_short v190, v186, s[70:71]
.Lp0t_in_6:
	s_add_i32 s93, s92, 7
	s_cmpk_ge_u32 s93, 0x1208
	s_cbranch_scc1 .Lp0t_in_7
	s_add_i32 s94, s93, 0xfffff800
	s_cmp_lt_u32 s94, 8
	s_cbranch_scc1 .Lp0t_in_7
	s_add_i32 s94, s93, -8
	s_cmpk_lt_u32 s93, 0x800
	s_cselect_b32 s94, s93, s94
	s_mul_i32 s94, s94, 0x800
	s_waitcnt lgkmcnt(8)
	v_cvt_pk_bf16_f32 v187, v171, v171
	v_add_u32_e32 v191, s94, v199
	global_store_short v191, v187, s[70:71]
.Lp0t_in_7:
	s_add_i32 s93, s92, 8
	s_cmpk_ge_u32 s93, 0x1208
	s_cbranch_scc1 .Lp0t_in_8
	s_add_i32 s94, s93, 0xfffff800
	s_cmp_lt_u32 s94, 8
	s_cbranch_scc1 .Lp0t_in_8
	s_add_i32 s94, s93, -8
	s_cmpk_lt_u32 s93, 0x800
	s_cselect_b32 s94, s93, s94
	s_mul_i32 s94, s94, 0x800
	s_waitcnt lgkmcnt(7)
	v_cvt_pk_bf16_f32 v180, v172, v172
	v_add_u32_e32 v188, s94, v199
	global_store_short v188, v180, s[70:71]
.Lp0t_in_8:
	s_add_i32 s93, s92, 9
	s_cmpk_ge_u32 s93, 0x1208
	s_cbranch_scc1 .Lp0t_in_9
	s_add_i32 s94, s93, 0xfffff800
	s_cmp_lt_u32 s94, 8
	s_cbranch_scc1 .Lp0t_in_9
	s_add_i32 s94, s93, -8
	s_cmpk_lt_u32 s93, 0x800
	s_cselect_b32 s94, s93, s94
	s_mul_i32 s94, s94, 0x800
	s_waitcnt lgkmcnt(6)
	v_cvt_pk_bf16_f32 v181, v173, v173
	v_add_u32_e32 v189, s94, v199
	global_store_short v189, v181, s[70:71]
.Lp0t_in_9:
	s_add_i32 s93, s92, 10
	s_cmpk_ge_u32 s93, 0x1208
	s_cbranch_scc1 .Lp0t_in_10
	s_add_i32 s94, s93, 0xfffff800
	s_cmp_lt_u32 s94, 8
	s_cbranch_scc1 .Lp0t_in_10
	s_add_i32 s94, s93, -8
	s_cmpk_lt_u32 s93, 0x800
	s_cselect_b32 s94, s93, s94
	s_mul_i32 s94, s94, 0x800
	s_waitcnt lgkmcnt(5)
	v_cvt_pk_bf16_f32 v182, v174, v174
	v_add_u32_e32 v190, s94, v199
	global_store_short v190, v182, s[70:71]
.Lp0t_in_10:
	s_add_i32 s93, s92, 11
	s_cmpk_ge_u32 s93, 0x1208
	s_cbranch_scc1 .Lp0t_in_11
	s_add_i32 s94, s93, 0xfffff800
	s_cmp_lt_u32 s94, 8
	s_cbranch_scc1 .Lp0t_in_11
	s_add_i32 s94, s93, -8
	s_cmpk_lt_u32 s93, 0x800
	s_cselect_b32 s94, s93, s94
	s_mul_i32 s94, s94, 0x800
	s_waitcnt lgkmcnt(4)
	v_cvt_pk_bf16_f32 v183, v175, v175
	v_add_u32_e32 v191, s94, v199
	global_store_short v191, v183, s[70:71]
.Lp0t_in_11:
	s_add_i32 s93, s92, 12
	s_cmpk_ge_u32 s93, 0x1208
	s_cbranch_scc1 .Lp0t_in_12
	s_add_i32 s94, s93, 0xfffff800
	s_cmp_lt_u32 s94, 8
	s_cbranch_scc1 .Lp0t_in_12
	s_add_i32 s94, s93, -8
	s_cmpk_lt_u32 s93, 0x800
	s_cselect_b32 s94, s93, s94
	s_mul_i32 s94, s94, 0x800
	s_waitcnt lgkmcnt(3)
	v_cvt_pk_bf16_f32 v184, v176, v176
	v_add_u32_e32 v188, s94, v199
	global_store_short v188, v184, s[70:71]
.Lp0t_in_12:
	s_add_i32 s93, s92, 13
	s_cmpk_ge_u32 s93, 0x1208
	s_cbranch_scc1 .Lp0t_in_13
	s_add_i32 s94, s93, 0xfffff800
	s_cmp_lt_u32 s94, 8
	s_cbranch_scc1 .Lp0t_in_13
	s_add_i32 s94, s93, -8
	s_cmpk_lt_u32 s93, 0x800
	s_cselect_b32 s94, s93, s94
	s_mul_i32 s94, s94, 0x800
	s_waitcnt lgkmcnt(2)
	v_cvt_pk_bf16_f32 v185, v177, v177
	v_add_u32_e32 v189, s94, v199
	global_store_short v189, v185, s[70:71]
.Lp0t_in_13:
	s_add_i32 s93, s92, 14
	s_cmpk_ge_u32 s93, 0x1208
	s_cbranch_scc1 .Lp0t_in_14
	s_add_i32 s94, s93, 0xfffff800
	s_cmp_lt_u32 s94, 8
	s_cbranch_scc1 .Lp0t_in_14
	s_add_i32 s94, s93, -8
	s_cmpk_lt_u32 s93, 0x800
	s_cselect_b32 s94, s93, s94
	s_mul_i32 s94, s94, 0x800
	s_waitcnt lgkmcnt(1)
	v_cvt_pk_bf16_f32 v186, v178, v178
	v_add_u32_e32 v190, s94, v199
	global_store_short v190, v186, s[70:71]
.Lp0t_in_14:
	s_add_i32 s93, s92, 15
	s_cmpk_ge_u32 s93, 0x1208
	s_cbranch_scc1 .Lp0t_in_15
	s_add_i32 s94, s93, 0xfffff800
	s_cmp_lt_u32 s94, 8
	s_cbranch_scc1 .Lp0t_in_15
	s_add_i32 s94, s93, -8
	s_cmpk_lt_u32 s93, 0x800
	s_cselect_b32 s94, s93, s94
	s_mul_i32 s94, s94, 0x800
	s_waitcnt lgkmcnt(0)
	v_cvt_pk_bf16_f32 v187, v179, v179
	v_add_u32_e32 v191, s94, v199
	global_store_short v191, v187, s[70:71]
.Lp0t_in_15:
	s_branch .LBB0_20
